# GEMM unit boundary: the two half-workgroups' epilogues un-aligned (pre/post-epilogue alignment barriers dropped, offset undone once at phase end) on top of the zeroing removal
# baseline (speedup 1.0000x reference)
.LBB0_49:
.LBB0_51:
	v_lshl_add_u32 v152, s55, 8, v135
	v_ashrrev_i32_e32 v153, 31, v152
	v_lshl_or_b32 v150, s54, 8, v156
	v_lshlrev_b64 v[154:155], 11, v[152:153]
	v_ashrrev_i32_e32 v151, 31, v150
	v_lshl_add_u64 v[154:155], s[8:9], 0, v[154:155]
	s_movk_i32 s0, 0x400
	v_lshl_add_u64 v[154:155], v[150:151], 1, v[154:155]
	v_cmp_gt_i32_e32 vcc, s0, v150
	s_and_saveexec_b64 s[0:1], vcc
	s_cbranch_execz .LBB0_53
	v_cvt_pk_bf16_f32 v120, v120, v121
	v_cvt_pk_bf16_f32 v121, v122, v123
	v_cvt_pk_bf16_f32 v122, v124, v125
	v_cvt_pk_bf16_f32 v123, v126, v127
	global_store_dwordx4 v[154:155], v[120:123], off

.LBB0_83:
	v_cvt_pk_bf16_f32 v4, v4, v5
	v_cvt_pk_bf16_f32 v5, v6, v7
	v_cvt_pk_bf16_f32 v6, v0, v1
	v_cvt_pk_bf16_f32 v7, v2, v3
	global_store_dwordx4 v[16:17], v[4:7], off offset:256
	s_or_b64 exec, exec, s[26:27]
	s_and_b64 vcc, exec, s[40:41]
	s_mov_b64 s[0:1], -1
	s_cbranch_vccnz .LBB0_34
.LBB0_84:
	s_branch .LBB0_33
.LBB0_86:
	s_waitcnt vmcnt(0)
	v_readlane_b32 s38, v255, 18
	v_readlane_b32 s39, v255, 19
	s_and_b64 vcc, exec, s[16:17]
	s_cbranch_vccz .Lunalign_0
	s_barrier
.Lunalign_0:
	s_barrier

.LBB0_105:
.LBB0_107:
	v_mul_f32_e32 v150, 0xbfb8aa3b, v124
	v_exp_f32_e32 v150, v150
	v_mul_f32_e32 v151, 0xbfb8aa3b, v125
	v_exp_f32_e32 v151, v151
	v_mul_f32_e32 v155, 0xbfb8aa3b, v126
	v_add_f32_e32 v150, 1.0, v150
	v_rcp_f32_e32 v158, v150
	v_add_f32_e32 v150, 1.0, v151
	v_rcp_f32_e32 v159, v150
	v_exp_f32_e32 v155, v155
	v_lshl_or_b32 v156, s52, 7, v152
	v_lshl_add_u32 v154, s53, 8, v135
	v_pk_mul_f32 v[124:125], v[124:125], v[158:159]
	v_mul_f32_e32 v158, 0xbfb8aa3b, v127
	v_exp_f32_e32 v158, v158
	v_pk_mul_f32 v[120:121], v[120:121], v[124:125]
	v_add_f32_e32 v124, 1.0, v155
	v_mul_f32_e32 v155, 0xbfb8aa3b, v116
	v_add_f32_e32 v125, 1.0, v158
	v_rcp_f32_e32 v124, v124
	v_rcp_f32_e32 v125, v125
	v_exp_f32_e32 v155, v155
	v_mul_f32_e32 v158, 0xbfb8aa3b, v117
	v_exp_f32_e32 v158, v158
	v_pk_mul_f32 v[124:125], v[126:127], v[124:125]
	v_add_f32_e32 v126, 1.0, v155
	v_mul_f32_e32 v155, 0xbfb8aa3b, v118
	v_add_f32_e32 v127, 1.0, v158
	v_exp_f32_e32 v155, v155
	v_mul_f32_e32 v158, 0xbfb8aa3b, v119
	v_exp_f32_e32 v159, v158
	v_rcp_f32_e32 v126, v126
	v_add_f32_e32 v155, 1.0, v155
	v_rcp_f32_e32 v127, v127
	v_rcp_f32_e32 v158, v155
	v_add_f32_e32 v155, 1.0, v159
	v_rcp_f32_e32 v159, v155
	v_pk_mul_f32 v[116:117], v[116:117], v[126:127]
	v_ashrrev_i32_e32 v157, 31, v156
	v_pk_mul_f32 v[116:117], v[112:113], v[116:117]
	v_pk_mul_f32 v[112:113], v[118:119], v[158:159]
	v_cvt_pk_bf16_f32 v116, v116, v117
	v_pk_mul_f32 v[118:119], v[114:115], v[112:113]
	v_mov_b64_e32 v[150:151], s[22:23]
	v_cvt_pk_bf16_f32 v117, v118, v119
	v_mul_f32_e32 v118, 0xbfb8aa3b, v108
	v_mul_f32_e32 v119, 0xbfb8aa3b, v109
	v_exp_f32_e32 v118, v118
	v_exp_f32_e32 v119, v119
	s_movk_i32 s26, 0x1600
	v_mad_i64_i32 v[160:161], s[24:25], v154, s26, v[150:151]
	v_pk_mul_f32 v[122:123], v[122:123], v[124:125]
	v_lshlrev_b64 v[112:113], 1, v[156:157]
	v_lshl_add_u64 v[124:125], v[160:161], 0, v[112:113]
	v_cvt_pk_bf16_f32 v114, v120, v121
	v_cvt_pk_bf16_f32 v115, v122, v123
	global_store_dwordx4 v[124:125], v[114:117], off
	s_and_b64 vcc, exec, s[40:41]
	s_nop 0
	v_add_f32_e32 v114, 1.0, v118
	v_add_f32_e32 v115, 1.0, v119
	v_rcp_f32_e32 v114, v114
	v_rcp_f32_e32 v115, v115
	v_or_b32_e32 v116, 16, v154
	v_mad_i64_i32 v[116:117], s[24:25], v116, s26, v[150:151]
	v_pk_mul_f32 v[108:109], v[108:109], v[114:115]
	v_mul_f32_e32 v114, 0xbfb8aa3b, v110
	v_mul_f32_e32 v115, 0xbfb8aa3b, v111
	v_exp_f32_e32 v114, v114
	v_exp_f32_e32 v115, v115
	v_pk_mul_f32 v[104:105], v[104:105], v[108:109]
	v_add_f32_e32 v108, 1.0, v114
	v_add_f32_e32 v109, 1.0, v115
	v_mul_f32_e32 v114, 0xbfb8aa3b, v100
	v_mul_f32_e32 v115, 0xbfb8aa3b, v101
	v_rcp_f32_e32 v108, v108
	v_rcp_f32_e32 v109, v109
	v_exp_f32_e32 v114, v114
	v_exp_f32_e32 v115, v115
	v_pk_mul_f32 v[108:109], v[110:111], v[108:109]
	v_add_f32_e32 v110, 1.0, v114
	v_add_f32_e32 v111, 1.0, v115
	v_mul_f32_e32 v114, 0xbfb8aa3b, v102
	v_mul_f32_e32 v115, 0xbfb8aa3b, v103
	v_exp_f32_e32 v114, v114
	v_exp_f32_e32 v115, v115
	v_rcp_f32_e32 v110, v110
	v_rcp_f32_e32 v111, v111
	v_add_f32_e32 v114, 1.0, v114
	v_add_f32_e32 v115, 1.0, v115
	v_rcp_f32_e32 v114, v114
	v_rcp_f32_e32 v115, v115
	v_pk_mul_f32 v[100:101], v[100:101], v[110:111]
	v_pk_mul_f32 v[106:107], v[106:107], v[108:109]
	v_pk_mul_f32 v[100:101], v[96:97], v[100:101]
	v_pk_mul_f32 v[96:97], v[102:103], v[114:115]
	v_lshl_add_u64 v[108:109], v[116:117], 0, v[112:113]
	v_pk_mul_f32 v[102:103], v[98:99], v[96:97]
	v_cvt_pk_bf16_f32 v98, v100, v101
	v_mul_f32_e32 v100, 0xbfb8aa3b, v92
	v_mul_f32_e32 v101, 0xbfb8aa3b, v93
	v_exp_f32_e32 v100, v100
	v_exp_f32_e32 v101, v101
	v_cvt_pk_bf16_f32 v96, v104, v105
	v_cvt_pk_bf16_f32 v97, v106, v107
	v_cvt_pk_bf16_f32 v99, v102, v103
	global_store_dwordx4 v[108:109], v[96:99], off
	s_nop 1
	v_add_f32_e32 v96, 1.0, v100
	v_add_f32_e32 v97, 1.0, v101
	v_rcp_f32_e32 v96, v96
	v_rcp_f32_e32 v97, v97
	v_or_b32_e32 v98, 32, v154
	v_mad_i64_i32 v[98:99], s[24:25], v98, s26, v[150:151]
	v_pk_mul_f32 v[92:93], v[92:93], v[96:97]
	v_mul_f32_e32 v96, 0xbfb8aa3b, v94
	v_mul_f32_e32 v97, 0xbfb8aa3b, v95
	v_exp_f32_e32 v96, v96
	v_exp_f32_e32 v97, v97
	v_pk_mul_f32 v[88:89], v[88:89], v[92:93]
	v_add_f32_e32 v92, 1.0, v96
	v_add_f32_e32 v93, 1.0, v97
	v_mul_f32_e32 v96, 0xbfb8aa3b, v84
	v_mul_f32_e32 v97, 0xbfb8aa3b, v85
	v_rcp_f32_e32 v92, v92
	v_rcp_f32_e32 v93, v93
	v_exp_f32_e32 v96, v96
	v_exp_f32_e32 v97, v97
	v_pk_mul_f32 v[92:93], v[94:95], v[92:93]
	v_add_f32_e32 v94, 1.0, v96
	v_add_f32_e32 v95, 1.0, v97
	v_mul_f32_e32 v96, 0xbfb8aa3b, v86
	v_mul_f32_e32 v97, 0xbfb8aa3b, v87
	v_exp_f32_e32 v96, v96
	v_exp_f32_e32 v97, v97
	v_rcp_f32_e32 v94, v94
	v_rcp_f32_e32 v95, v95
	v_add_f32_e32 v96, 1.0, v96
	v_add_f32_e32 v97, 1.0, v97
	v_rcp_f32_e32 v96, v96
	v_rcp_f32_e32 v97, v97
	v_pk_mul_f32 v[84:85], v[84:85], v[94:95]
	v_pk_mul_f32 v[90:91], v[90:91], v[92:93]
	v_pk_mul_f32 v[84:85], v[80:81], v[84:85]
	v_pk_mul_f32 v[80:81], v[86:87], v[96:97]
	v_lshl_add_u64 v[92:93], v[98:99], 0, v[112:113]
	v_pk_mul_f32 v[86:87], v[82:83], v[80:81]
	v_cvt_pk_bf16_f32 v82, v84, v85
	v_mul_f32_e32 v84, 0xbfb8aa3b, v76
	v_mul_f32_e32 v85, 0xbfb8aa3b, v77
	v_exp_f32_e32 v84, v84
	v_exp_f32_e32 v85, v85
	v_cvt_pk_bf16_f32 v80, v88, v89
	v_cvt_pk_bf16_f32 v81, v90, v91
	v_cvt_pk_bf16_f32 v83, v86, v87
	global_store_dwordx4 v[92:93], v[80:83], off
	s_nop 1
	v_add_f32_e32 v80, 1.0, v84
	v_add_f32_e32 v81, 1.0, v85
	v_rcp_f32_e32 v80, v80
	v_rcp_f32_e32 v81, v81
	v_or_b32_e32 v82, 48, v154
	v_mad_i64_i32 v[82:83], s[24:25], v82, s26, v[150:151]
	v_pk_mul_f32 v[76:77], v[76:77], v[80:81]
	v_mul_f32_e32 v80, 0xbfb8aa3b, v78
	v_mul_f32_e32 v81, 0xbfb8aa3b, v79
	v_exp_f32_e32 v80, v80
	v_exp_f32_e32 v81, v81
	v_pk_mul_f32 v[72:73], v[72:73], v[76:77]
	v_add_f32_e32 v76, 1.0, v80
	v_add_f32_e32 v77, 1.0, v81
	v_mul_f32_e32 v80, 0xbfb8aa3b, v68
	v_mul_f32_e32 v81, 0xbfb8aa3b, v69
	v_rcp_f32_e32 v76, v76
	v_rcp_f32_e32 v77, v77
	v_exp_f32_e32 v80, v80
	v_exp_f32_e32 v81, v81
	v_pk_mul_f32 v[76:77], v[78:79], v[76:77]
	v_add_f32_e32 v78, 1.0, v80
	v_add_f32_e32 v79, 1.0, v81
	v_mul_f32_e32 v80, 0xbfb8aa3b, v70
	v_mul_f32_e32 v81, 0xbfb8aa3b, v71
	v_exp_f32_e32 v80, v80
	v_exp_f32_e32 v81, v81
	v_rcp_f32_e32 v78, v78
	v_rcp_f32_e32 v79, v79
	v_add_f32_e32 v80, 1.0, v80
	v_add_f32_e32 v81, 1.0, v81
	v_rcp_f32_e32 v80, v80
	v_rcp_f32_e32 v81, v81
	v_pk_mul_f32 v[68:69], v[68:69], v[78:79]
	v_pk_mul_f32 v[74:75], v[74:75], v[76:77]
	v_pk_mul_f32 v[68:69], v[64:65], v[68:69]
	v_pk_mul_f32 v[64:65], v[70:71], v[80:81]
	v_lshl_add_u64 v[76:77], v[82:83], 0, v[112:113]
	v_pk_mul_f32 v[70:71], v[66:67], v[64:65]
	v_cvt_pk_bf16_f32 v66, v68, v69
	v_mul_f32_e32 v68, 0xbfb8aa3b, v60
	v_mul_f32_e32 v69, 0xbfb8aa3b, v61
	v_exp_f32_e32 v68, v68
	v_exp_f32_e32 v69, v69
	v_cvt_pk_bf16_f32 v64, v72, v73
	v_cvt_pk_bf16_f32 v65, v74, v75
	v_cvt_pk_bf16_f32 v67, v70, v71
	global_store_dwordx4 v[76:77], v[64:67], off
	s_nop 1
	v_add_f32_e32 v64, 1.0, v68
	v_add_f32_e32 v65, 1.0, v69
	v_rcp_f32_e32 v64, v64
	v_rcp_f32_e32 v65, v65
	v_add_u32_e32 v66, 0x80, v154
	v_mad_i64_i32 v[66:67], s[24:25], v66, s26, v[150:151]
	v_pk_mul_f32 v[60:61], v[60:61], v[64:65]
	v_mul_f32_e32 v64, 0xbfb8aa3b, v62
	v_mul_f32_e32 v65, 0xbfb8aa3b, v63
	v_exp_f32_e32 v64, v64
	v_exp_f32_e32 v65, v65
	v_pk_mul_f32 v[56:57], v[56:57], v[60:61]
	v_add_f32_e32 v60, 1.0, v64
	v_add_f32_e32 v61, 1.0, v65
	v_mul_f32_e32 v64, 0xbfb8aa3b, v52
	v_mul_f32_e32 v65, 0xbfb8aa3b, v53
	v_rcp_f32_e32 v60, v60
	v_rcp_f32_e32 v61, v61
	v_exp_f32_e32 v64, v64
	v_exp_f32_e32 v65, v65
	v_pk_mul_f32 v[60:61], v[62:63], v[60:61]
	v_add_f32_e32 v62, 1.0, v64
	v_add_f32_e32 v63, 1.0, v65
	v_mul_f32_e32 v64, 0xbfb8aa3b, v54
	v_mul_f32_e32 v65, 0xbfb8aa3b, v55
	v_exp_f32_e32 v64, v64
	v_exp_f32_e32 v65, v65
	v_rcp_f32_e32 v62, v62
	v_rcp_f32_e32 v63, v63
	v_add_f32_e32 v64, 1.0, v64
	v_add_f32_e32 v65, 1.0, v65
	v_rcp_f32_e32 v64, v64
	v_rcp_f32_e32 v65, v65
	v_pk_mul_f32 v[52:53], v[52:53], v[62:63]
	v_pk_mul_f32 v[58:59], v[58:59], v[60:61]
	v_pk_mul_f32 v[52:53], v[48:49], v[52:53]
	v_pk_mul_f32 v[48:49], v[54:55], v[64:65]
	v_lshl_add_u64 v[60:61], v[66:67], 0, v[112:113]
	v_pk_mul_f32 v[54:55], v[50:51], v[48:49]
	v_cvt_pk_bf16_f32 v50, v52, v53
	v_mul_f32_e32 v52, 0xbfb8aa3b, v44
	v_mul_f32_e32 v53, 0xbfb8aa3b, v45
	v_exp_f32_e32 v52, v52
	v_exp_f32_e32 v53, v53
	v_cvt_pk_bf16_f32 v48, v56, v57
	v_cvt_pk_bf16_f32 v49, v58, v59
	v_cvt_pk_bf16_f32 v51, v54, v55
	global_store_dwordx4 v[60:61], v[48:51], off
	s_nop 1
	v_add_f32_e32 v48, 1.0, v52
	v_add_f32_e32 v49, 1.0, v53
	v_rcp_f32_e32 v48, v48
	v_rcp_f32_e32 v49, v49
	v_add_u32_e32 v50, 0x90, v154
	v_mad_i64_i32 v[50:51], s[24:25], v50, s26, v[150:151]
	v_pk_mul_f32 v[44:45], v[44:45], v[48:49]
	v_mul_f32_e32 v48, 0xbfb8aa3b, v46
	v_mul_f32_e32 v49, 0xbfb8aa3b, v47
	v_exp_f32_e32 v48, v48
	v_exp_f32_e32 v49, v49
	v_pk_mul_f32 v[40:41], v[40:41], v[44:45]
	v_add_f32_e32 v44, 1.0, v48
	v_add_f32_e32 v45, 1.0, v49
	v_mul_f32_e32 v48, 0xbfb8aa3b, v36
	v_mul_f32_e32 v49, 0xbfb8aa3b, v37
	v_rcp_f32_e32 v44, v44
	v_rcp_f32_e32 v45, v45
	v_exp_f32_e32 v48, v48
	v_exp_f32_e32 v49, v49
	v_pk_mul_f32 v[44:45], v[46:47], v[44:45]
	v_add_f32_e32 v46, 1.0, v48
	v_add_f32_e32 v47, 1.0, v49
	v_mul_f32_e32 v48, 0xbfb8aa3b, v38
	v_mul_f32_e32 v49, 0xbfb8aa3b, v39
	v_exp_f32_e32 v48, v48
	v_exp_f32_e32 v49, v49
	v_rcp_f32_e32 v46, v46
	v_rcp_f32_e32 v47, v47
	v_add_f32_e32 v48, 1.0, v48
	v_add_f32_e32 v49, 1.0, v49
	v_rcp_f32_e32 v48, v48
	v_rcp_f32_e32 v49, v49
	v_pk_mul_f32 v[36:37], v[36:37], v[46:47]
	v_pk_mul_f32 v[42:43], v[42:43], v[44:45]
	v_pk_mul_f32 v[36:37], v[32:33], v[36:37]
	v_pk_mul_f32 v[32:33], v[38:39], v[48:49]
	v_lshl_add_u64 v[44:45], v[50:51], 0, v[112:113]
	v_pk_mul_f32 v[38:39], v[34:35], v[32:33]
	v_cvt_pk_bf16_f32 v34, v36, v37
	v_mul_f32_e32 v36, 0xbfb8aa3b, v28
	v_mul_f32_e32 v37, 0xbfb8aa3b, v29
	v_exp_f32_e32 v36, v36
	v_exp_f32_e32 v37, v37
	v_cvt_pk_bf16_f32 v32, v40, v41
	v_cvt_pk_bf16_f32 v33, v42, v43
	v_cvt_pk_bf16_f32 v35, v38, v39
	global_store_dwordx4 v[44:45], v[32:35], off
	s_nop 1
	v_add_f32_e32 v32, 1.0, v36
	v_add_f32_e32 v33, 1.0, v37
	v_rcp_f32_e32 v32, v32
	v_rcp_f32_e32 v33, v33
	v_add_u32_e32 v34, 0xa0, v154
	v_mad_i64_i32 v[34:35], s[24:25], v34, s26, v[150:151]
	v_pk_mul_f32 v[28:29], v[28:29], v[32:33]
	v_mul_f32_e32 v32, 0xbfb8aa3b, v30
	v_mul_f32_e32 v33, 0xbfb8aa3b, v31
	v_exp_f32_e32 v32, v32
	v_exp_f32_e32 v33, v33
	v_pk_mul_f32 v[24:25], v[24:25], v[28:29]
	v_add_f32_e32 v28, 1.0, v32
	v_add_f32_e32 v29, 1.0, v33
	v_mul_f32_e32 v32, 0xbfb8aa3b, v20
	v_mul_f32_e32 v33, 0xbfb8aa3b, v21
	v_rcp_f32_e32 v28, v28
	v_rcp_f32_e32 v29, v29
	v_exp_f32_e32 v32, v32
	v_exp_f32_e32 v33, v33
	v_pk_mul_f32 v[28:29], v[30:31], v[28:29]
	v_add_f32_e32 v30, 1.0, v32
	v_add_f32_e32 v31, 1.0, v33
	v_mul_f32_e32 v32, 0xbfb8aa3b, v22
	v_mul_f32_e32 v33, 0xbfb8aa3b, v23
	v_exp_f32_e32 v32, v32
	v_exp_f32_e32 v33, v33
	v_rcp_f32_e32 v30, v30
	v_rcp_f32_e32 v31, v31
	v_add_f32_e32 v32, 1.0, v32
	v_add_f32_e32 v33, 1.0, v33
	v_rcp_f32_e32 v32, v32
	v_rcp_f32_e32 v33, v33
	v_pk_mul_f32 v[20:21], v[20:21], v[30:31]
	v_pk_mul_f32 v[26:27], v[26:27], v[28:29]
	v_pk_mul_f32 v[20:21], v[16:17], v[20:21]
	v_pk_mul_f32 v[16:17], v[22:23], v[32:33]
	v_lshl_add_u64 v[28:29], v[34:35], 0, v[112:113]
	v_pk_mul_f32 v[22:23], v[18:19], v[16:17]
	v_cvt_pk_bf16_f32 v18, v20, v21
	v_mul_f32_e32 v20, 0xbfb8aa3b, v12
	v_mul_f32_e32 v21, 0xbfb8aa3b, v13
	v_exp_f32_e32 v20, v20
	v_exp_f32_e32 v21, v21
	v_cvt_pk_bf16_f32 v16, v24, v25
	v_cvt_pk_bf16_f32 v17, v26, v27
	v_cvt_pk_bf16_f32 v19, v22, v23
	global_store_dwordx4 v[28:29], v[16:19], off
	s_nop 1
	v_add_f32_e32 v16, 1.0, v20
	v_add_f32_e32 v17, 1.0, v21
	v_rcp_f32_e32 v16, v16
	v_rcp_f32_e32 v17, v17
	v_add_u32_e32 v18, 0xb0, v154
	v_mad_i64_i32 v[18:19], s[24:25], v18, s26, v[150:151]
	v_pk_mul_f32 v[12:13], v[12:13], v[16:17]
	v_mul_f32_e32 v16, 0xbfb8aa3b, v14
	v_mul_f32_e32 v17, 0xbfb8aa3b, v15
	v_exp_f32_e32 v16, v16
	v_exp_f32_e32 v17, v17
	v_pk_mul_f32 v[8:9], v[8:9], v[12:13]
	s_mov_b64 s[24:25], -1
	v_add_f32_e32 v12, 1.0, v16
	v_add_f32_e32 v13, 1.0, v17
	v_mul_f32_e32 v16, 0xbfb8aa3b, v4
	v_mul_f32_e32 v17, 0xbfb8aa3b, v5
	v_rcp_f32_e32 v12, v12
	v_rcp_f32_e32 v13, v13
	v_exp_f32_e32 v16, v16
	v_exp_f32_e32 v17, v17
	v_pk_mul_f32 v[12:13], v[14:15], v[12:13]
	v_add_f32_e32 v14, 1.0, v16
	v_add_f32_e32 v15, 1.0, v17
	v_mul_f32_e32 v16, 0xbfb8aa3b, v6
	v_mul_f32_e32 v17, 0xbfb8aa3b, v7
	v_exp_f32_e32 v16, v16
	v_exp_f32_e32 v17, v17
	v_rcp_f32_e32 v14, v14
	v_rcp_f32_e32 v15, v15
	v_add_f32_e32 v16, 1.0, v16
	v_add_f32_e32 v17, 1.0, v17
	v_rcp_f32_e32 v16, v16
	v_rcp_f32_e32 v17, v17
	v_pk_mul_f32 v[4:5], v[4:5], v[14:15]
	v_pk_mul_f32 v[10:11], v[10:11], v[12:13]
	v_pk_mul_f32 v[4:5], v[0:1], v[4:5]
	v_pk_mul_f32 v[0:1], v[6:7], v[16:17]
	v_lshl_add_u64 v[12:13], v[18:19], 0, v[112:113]
	v_pk_mul_f32 v[6:7], v[2:3], v[0:1]
	v_cvt_pk_bf16_f32 v0, v8, v9
	v_cvt_pk_bf16_f32 v1, v10, v11
	v_cvt_pk_bf16_f32 v2, v4, v5
	v_cvt_pk_bf16_f32 v3, v6, v7
	global_store_dwordx4 v[12:13], v[0:3], off
	s_cbranch_vccnz .LBB0_94
	s_branch .LBB0_93

.LBB0_141:
.LBB0_143:
	v_lshl_add_u32 v152, s53, 8, v135
	v_ashrrev_i32_e32 v153, 31, v152
	v_lshl_or_b32 v150, s52, 8, v156
	v_lshlrev_b64 v[154:155], 11, v[152:153]
	v_ashrrev_i32_e32 v151, 31, v150
	v_lshl_add_u64 v[154:155], s[4:5], 0, v[154:155]
	s_movk_i32 s0, 0x400
	v_lshl_add_u64 v[154:155], v[150:151], 1, v[154:155]
	v_cmp_gt_i32_e32 vcc, s0, v150
	s_and_saveexec_b64 s[0:1], vcc
	s_cbranch_execz .LBB0_145
	v_cvt_pk_bf16_f32 v120, v120, v121
	v_cvt_pk_bf16_f32 v121, v122, v123
	v_cvt_pk_bf16_f32 v122, v124, v125
	v_cvt_pk_bf16_f32 v123, v126, v127
	global_store_dwordx4 v[154:155], v[120:123], off

.LBB0_175:
	v_cvt_pk_bf16_f32 v4, v4, v5
	v_cvt_pk_bf16_f32 v5, v6, v7
	v_cvt_pk_bf16_f32 v6, v0, v1
	v_cvt_pk_bf16_f32 v7, v2, v3
	global_store_dwordx4 v[16:17], v[4:7], off offset:256
	s_or_b64 exec, exec, s[26:27]
	s_and_b64 vcc, exec, s[40:41]
	s_mov_b64 s[0:1], -1
	s_cbranch_vccnz .LBB0_126
.LBB0_176:
	s_branch .LBB0_125

.LBB0_341:
.LBB0_343:
	v_lshl_add_u32 v156, s53, 8, v135
	v_lshl_or_b32 v150, s52, 8, v154
	v_mov_b64_e32 v[152:153], s[22:23]
	v_ashrrev_i32_e32 v151, 31, v150
	v_mad_i64_i32 v[152:153], s[0:1], v156, s93, v[152:153]
	v_lshl_add_u64 v[152:153], v[150:151], 1, v[152:153]
	v_cmp_gt_i32_e32 vcc, s94, v150
	s_and_saveexec_b64 s[0:1], vcc
	s_cbranch_execz .LBB0_345
	v_cvt_pk_bf16_f32 v120, v120, v121
	v_cvt_pk_bf16_f32 v121, v122, v123
	v_cvt_pk_bf16_f32 v122, v124, v125
	v_cvt_pk_bf16_f32 v123, v126, v127
	global_store_dwordx4 v[152:153], v[120:123], off

.LBB0_375:
	v_cvt_pk_bf16_f32 v4, v4, v5
	v_cvt_pk_bf16_f32 v5, v6, v7
	v_cvt_pk_bf16_f32 v6, v0, v1
	v_cvt_pk_bf16_f32 v7, v2, v3
	global_store_dwordx4 v[16:17], v[4:7], off offset:256
	s_or_b64 exec, exec, s[26:27]
	s_and_b64 vcc, exec, s[40:41]
	s_mov_b64 s[0:1], -1
	s_cbranch_vccnz .LBB0_326
.LBB0_376:
	s_branch .LBB0_325
